# SGU LayerNorm loads of iterations 1..3 issued at item start (one memory latency per item instead of four)
# speedup vs baseline: 1.0152x; 1.0059x over previous
.LBB0_977:
	s_and_b32 s39, s38, 3
	s_and_b32 s41, s26, 0xffffff80
	s_cmpk_gt_i32 s41, 0x7fff
	s_cselect_b64 s[24:25], -1, 0
	s_and_b64 s[0:1], s[24:25], exec
	s_cselect_b32 s0, s29, 0x3500000
	v_or_b32_e32 v70, s41, v35
	s_add_u32 s0, s86, s0
	v_ashrrev_i32_e32 v71, 31, v70
	s_addc_u32 s1, s87, 0
	s_lshl_b32 s6, s39, 15
	v_lshlrev_b64 v[2:3], 6, v[70:71]
	s_add_u32 s0, s0, s6
	v_lshl_add_u64 v[2:3], s[14:15], 0, v[2:3]
	s_addc_u32 s1, s1, 0
	s_lshl_b32 s16, s39, 8
	global_load_dwordx4 v[26:29], v[2:3], off offset:32
	global_load_dwordx4 v[30:33], v[2:3], off offset:16
	global_load_dwordx4 v[112:115], v[2:3], off offset:48
	v_lshl_add_u64 v[68:69], v[44:45], 0, s[16:17]
	v_lshlrev_b64 v[4:5], 10, v[70:71]
	v_lshl_add_u64 v[4:5], v[68:69], 0, v[4:5]
	global_load_dwordx4 v[116:119], v[2:3], off
	global_load_dwordx4 v[120:123], v[4:5], off nt
	v_add_u32_e32 v64, s41, v34
	v_ashrrev_i32_e32 v65, 31, v64
	v_lshlrev_b64 v[2:3], 10, v[64:65]
	v_lshl_add_u64 v[2:3], s[10:11], 0, v[2:3]
	v_lshlrev_b32_e32 v36, 1, v40
	v_mov_b32_e32 v49, v37
	s_mov_b32 s7, s17
	s_lshl_b32 s6, s39, 9
	v_lshl_add_u64 v[4:5], s[0:1], 0, v[38:39]
	v_lshl_add_u64 v[2:3], v[2:3], 0, s[16:17]
	v_lshl_add_u64 v[6:7], v[46:47], 0, s[6:7]
	v_lshl_add_u64 v[4:5], v[4:5], 0, v[36:37]
	v_lshl_add_u64 v[50:51], v[2:3], 0, v[48:49]
	global_load_dwordx4 v[18:21], v[6:7], off offset:16
	global_load_dwordx4 v[22:25], v[6:7], off
	global_load_dwordx4 v[14:17], v[4:5], off
	global_load_dwordx4 v[10:13], v[4:5], off offset:64
	s_nop 0
	global_load_dwordx4 v[6:9], v[4:5], off offset:128
	s_nop 0
	global_load_dwordx4 v[2:5], v[4:5], off offset:192
	s_nop 0
	global_load_dwordx2 v[66:67], v[50:51], off nt
	global_load_dwordx2 v[62:63], v[50:51], off offset:32 nt
	global_load_dwordx2 v[60:61], v[50:51], off offset:64 nt
	global_load_dwordx2 v[58:59], v[50:51], off offset:96 nt
	global_load_dwordx2 v[56:57], v[50:51], off offset:128 nt
	global_load_dwordx2 v[54:55], v[50:51], off offset:160 nt
	global_load_dwordx2 v[52:53], v[50:51], off offset:192 nt
	s_nop 0
	global_load_dwordx2 v[50:51], v[50:51], off offset:224 nt
	v_or_b32_e32 v236, s41, v43
	v_ashrrev_i32_e32 v237, 31, v236
	v_lshlrev_b64 v[238:239], 6, v[236:237]
	v_lshlrev_b64 v[240:241], 10, v[236:237]
	v_lshl_add_u64 v[238:239], s[14:15], 0, v[238:239]
	v_lshl_add_u64 v[240:241], v[68:69], 0, v[240:241]
	s_nop 0
	global_load_dwordx4 v[164:167], v[238:239], off
	global_load_dwordx4 v[168:171], v[238:239], off offset:32
	global_load_dwordx4 v[172:175], v[238:239], off offset:16
	global_load_dwordx4 v[176:179], v[238:239], off offset:48
	global_load_dwordx4 v[180:183], v[240:241], off nt
	v_or_b32_e32 v242, s41, v72
	v_ashrrev_i32_e32 v243, 31, v242
	v_lshlrev_b64 v[192:193], 6, v[242:243]
	v_lshlrev_b64 v[254:255], 10, v[242:243]
	v_lshl_add_u64 v[192:193], s[14:15], 0, v[192:193]
	v_lshl_add_u64 v[254:255], v[68:69], 0, v[254:255]
	s_nop 0
	global_load_dwordx4 v[184:187], v[192:193], off
	global_load_dwordx4 v[188:191], v[192:193], off offset:32
	global_load_dwordx4 v[198:201], v[192:193], off offset:16
	global_load_dwordx4 v[202:205], v[192:193], off offset:48
	global_load_dwordx4 v[206:209], v[254:255], off nt
	v_add_u32_e32 v236, s41, v73
	v_ashrrev_i32_e32 v237, 31, v236
	v_lshlrev_b64 v[238:239], 6, v[236:237]
	v_lshlrev_b64 v[240:241], 10, v[236:237]
	v_lshl_add_u64 v[238:239], s[14:15], 0, v[238:239]
	v_lshl_add_u64 v[240:241], v[68:69], 0, v[240:241]
	s_nop 0
	global_load_dwordx4 v[212:215], v[238:239], off
	global_load_dwordx4 v[220:223], v[238:239], off offset:32
	global_load_dwordx4 v[224:227], v[238:239], off offset:16
	global_load_dwordx4 v[228:231], v[238:239], off offset:48
	global_load_dwordx4 v[232:235], v[240:241], off nt
	s_lshl_b32 s40, s39, 7
	s_cmp_lt_i32 s41, 0x8000
	s_waitcnt vmcnt(33)
	v_pk_add_f32 v[26:27], v[26:27], v[28:29]
	s_waitcnt vmcnt(32)
	v_pk_add_f32 v[30:31], v[30:31], v[32:33]
	s_waitcnt vmcnt(31)
	v_pk_add_f32 v[28:29], v[112:113], v[114:115]
	s_waitcnt vmcnt(29)
	v_lshlrev_b32_e32 v112, 16, v121
	v_pk_add_f32 v[26:27], v[26:27], v[28:29]
	v_pk_add_f32 v[28:29], v[116:117], v[118:119]
	v_and_b32_e32 v113, 0xffff0000, v121
	v_pk_add_f32 v[28:29], v[28:29], v[30:31]
	v_lshlrev_b32_e32 v32, 16, v120
	v_pk_add_f32 v[26:27], v[28:29], v[26:27]
	v_and_b32_e32 v33, 0xffff0000, v120
	v_pk_mul_f32 v[26:27], v[26:27], s[20:21] op_sel_hi:[1,0]
	v_lshlrev_b32_e32 v114, 16, v122
	v_fma_f32 v28, -v26, v26, v27
	v_max_f32_e32 v28, 0, v28
	v_add_f32_e32 v28, 0x358637bd, v28
	v_mul_f32_e32 v29, 0x4f800000, v28
	v_cmp_gt_f32_e32 vcc, s30, v28
	v_pk_add_f32 v[30:31], v[112:113], v[26:27] op_sel_hi:[1,0] neg_lo:[0,1] neg_hi:[0,1]
	v_and_b32_e32 v115, 0xffff0000, v122
	v_cndmask_b32_e32 v36, v28, v29, vcc
	v_sqrt_f32_e32 v49, v36
	v_lshlrev_b32_e32 v116, 16, v123
	v_and_b32_e32 v117, 0xffff0000, v123
	v_pk_add_f32 v[28:29], v[32:33], v[26:27] op_sel_hi:[1,0] neg_lo:[0,1] neg_hi:[0,1]
	v_add_u32_e32 v65, -1, v49
	v_add_u32_e32 v111, 1, v49
	v_fma_f32 v112, -v65, v49, v36
	v_fma_f32 v113, -v111, v49, v36
	v_cmp_ge_f32_e64 s[0:1], 0, v112
	v_pk_add_f32 v[32:33], v[114:115], v[26:27] op_sel_hi:[1,0] neg_lo:[0,1] neg_hi:[0,1]
	v_pk_add_f32 v[26:27], v[116:117], v[26:27] op_sel_hi:[1,0] neg_lo:[0,1] neg_hi:[0,1]
	v_cndmask_b32_e64 v49, v49, v65, s[0:1]
	v_cmp_lt_f32_e64 s[0:1], 0, v113
	s_nop 1
	v_cndmask_b32_e64 v49, v49, v111, s[0:1]
	v_mul_f32_e32 v65, 0x37800000, v49
	v_cndmask_b32_e32 v49, v49, v65, vcc
	v_cmp_class_f32_e32 vcc, v36, v74
	s_nop 1
	v_cndmask_b32_e32 v36, v49, v36, vcc
	v_div_scale_f32 v49, s[0:1], v36, v36, 1.0
	v_rcp_f32_e32 v65, v49
	v_div_scale_f32 v111, vcc, 1.0, v36, 1.0
	v_fma_f32 v112, -v49, v65, 1.0
	v_fmac_f32_e32 v65, v112, v65
	v_mul_f32_e32 v112, v111, v65
	v_fma_f32 v113, -v49, v112, v111
	v_fmac_f32_e32 v112, v113, v65
	v_fma_f32 v49, -v49, v112, v111
	v_div_fmas_f32 v49, v49, v65, v112
	v_div_fixup_f32 v36, v49, v36, 1.0
	v_pk_mul_f32 v[28:29], v[28:29], v[36:37] op_sel_hi:[1,0]
	v_pk_mul_f32 v[112:113], v[30:31], v[36:37] op_sel_hi:[1,0]
	v_pk_mul_f32 v[114:115], v[32:33], v[36:37] op_sel_hi:[1,0]
	v_pk_mul_f32 v[116:117], v[26:27], v[36:37] op_sel_hi:[1,0]
	s_waitcnt vmcnt(27)
	v_pk_mul_f32 v[30:31], v[22:23], v[28:29]
	v_pk_mul_f32 v[32:33], v[24:25], v[112:113]
	v_pk_mul_f32 v[26:27], v[18:19], v[114:115]
	v_pk_mul_f32 v[28:29], v[20:21], v[116:117]
	v_lshlrev_b32_e32 v36, 2, v42
	s_cbranch_scc1 .LBB0_979
	v_lshlrev_b64 v[70:71], 11, v[70:71]
	v_lshl_add_u64 v[70:71], s[18:19], 0, v[70:71]
	s_lshl_b32 s16, s40, 2
	v_lshl_add_u64 v[70:71], v[70:71], 0, s[16:17]
	v_lshl_add_u64 v[70:71], v[70:71], 0, v[36:37]
	v_lshl_add_u64 v[112:113], v[70:71], 0, s[22:23]
	v_add_co_u32_e32 v70, vcc, 0xfc000000, v70
	s_nop 1
	v_addc_co_u32_e32 v71, vcc, -1, v71, vcc
	global_store_dwordx4 v[70:71], v[30:33], off
	global_store_dwordx4 v[112:113], v[26:29], off offset:16
.LBB0_979:
	v_or_b32_e32 v70, s41, v43
	v_ashrrev_i32_e32 v71, 31, v70
	v_lshlrev_b64 v[112:113], 6, v[70:71]
	v_lshlrev_b64 v[124:125], 10, v[70:71]
	v_lshl_add_u64 v[126:127], s[14:15], 0, v[112:113]
	s_waitcnt vmcnt(10)
	v_mov_b32_e32 v112, v164
	v_mov_b32_e32 v113, v165
	v_mov_b32_e32 v114, v166
	v_mov_b32_e32 v115, v167
	v_mov_b32_e32 v116, v168
	v_mov_b32_e32 v117, v169
	v_mov_b32_e32 v118, v170
	v_mov_b32_e32 v119, v171
	v_mov_b32_e32 v120, v172
	v_mov_b32_e32 v121, v173
	v_mov_b32_e32 v122, v174
	v_mov_b32_e32 v123, v175
	v_lshl_add_u64 v[128:129], v[68:69], 0, v[124:125]
	v_mov_b32_e32 v124, v176
	v_mov_b32_e32 v125, v177
	v_mov_b32_e32 v126, v178
	v_mov_b32_e32 v127, v179
	s_nop 0
	v_mov_b32_e32 v128, v180
	v_mov_b32_e32 v129, v181
	v_mov_b32_e32 v130, v182
	v_mov_b32_e32 v131, v183
	v_bfe_u32 v49, v30, 16, 1
	v_bfe_u32 v65, v31, 16, 1
	v_bfe_u32 v111, v32, 16, 1
	v_bfe_u32 v132, v33, 16, 1
	v_bfe_u32 v133, v26, 16, 1
	v_bfe_u32 v134, v27, 16, 1
	v_bfe_u32 v135, v28, 16, 1
	v_bfe_u32 v136, v29, 16, 1
	v_add3_u32 v30, v30, v49, s28
	v_add3_u32 v31, v31, v65, s28
	v_add3_u32 v32, v32, v111, s28
	v_add3_u32 v33, v33, v132, s28
	v_add3_u32 v26, v26, v133, s28
	v_add3_u32 v27, v27, v134, s28
	v_add3_u32 v28, v28, v135, s28
	v_add3_u32 v29, v29, v136, s28
	ds_write_b16_d16_hi v75, v30
	ds_write_b16_d16_hi v75, v31 offset:272
	ds_write_b16_d16_hi v75, v32 offset:544
	ds_write_b16_d16_hi v75, v33 offset:816
	ds_write_b16_d16_hi v75, v26 offset:1088
	ds_write_b16_d16_hi v75, v27 offset:1360
	ds_write_b16_d16_hi v75, v28 offset:1632
	ds_write_b16_d16_hi v75, v29 offset:1904
	v_cndmask_b32_e64 v137, 0, 1, s[24:25]
	v_cmp_ne_u32_e64 s[0:1], 1, v137
	v_pk_add_f32 v[26:27], v[112:113], v[114:115]
	v_pk_add_f32 v[30:31], v[116:117], v[118:119]
	v_pk_add_f32 v[28:29], v[120:121], v[122:123]
	v_pk_add_f32 v[32:33], v[124:125], v[126:127]
	v_pk_add_f32 v[26:27], v[26:27], v[28:29]
	v_pk_add_f32 v[28:29], v[30:31], v[32:33]
	v_lshlrev_b32_e32 v112, 16, v128
	v_pk_add_f32 v[26:27], v[26:27], v[28:29]
	v_and_b32_e32 v113, 0xffff0000, v128
	v_pk_mul_f32 v[26:27], v[26:27], s[20:21] op_sel_hi:[1,0]
	v_lshlrev_b32_e32 v114, 16, v129
	v_fma_f32 v28, -v26, v26, v27
	v_max_f32_e32 v28, 0, v28
	v_add_f32_e32 v28, 0x358637bd, v28
	v_mul_f32_e32 v29, 0x4f800000, v28
	v_cmp_gt_f32_e32 vcc, s30, v28
	v_and_b32_e32 v115, 0xffff0000, v129
	v_pk_add_f32 v[30:31], v[114:115], v[26:27] op_sel_hi:[1,0] neg_lo:[0,1] neg_hi:[0,1]
	v_cndmask_b32_e32 v49, v28, v29, vcc
	v_sqrt_f32_e32 v65, v49
	v_pk_add_f32 v[28:29], v[112:113], v[26:27] op_sel_hi:[1,0] neg_lo:[0,1] neg_hi:[0,1]
	v_lshlrev_b32_e32 v116, 16, v130
	v_and_b32_e32 v117, 0xffff0000, v130
	v_add_u32_e32 v111, -1, v65
	v_add_u32_e32 v112, 1, v65
	v_fma_f32 v113, -v111, v65, v49
	v_fma_f32 v114, -v112, v65, v49
	v_cmp_ge_f32_e64 s[6:7], 0, v113
	v_lshlrev_b32_e32 v118, 16, v131
	v_and_b32_e32 v119, 0xffff0000, v131
	v_cndmask_b32_e64 v65, v65, v111, s[6:7]
	v_cmp_lt_f32_e64 s[6:7], 0, v114
	v_pk_add_f32 v[32:33], v[116:117], v[26:27] op_sel_hi:[1,0] neg_lo:[0,1] neg_hi:[0,1]
	v_pk_add_f32 v[26:27], v[118:119], v[26:27] op_sel_hi:[1,0] neg_lo:[0,1] neg_hi:[0,1]
	v_cndmask_b32_e64 v65, v65, v112, s[6:7]
	v_mul_f32_e32 v111, 0x37800000, v65
	v_cndmask_b32_e32 v65, v65, v111, vcc
	v_cmp_class_f32_e32 vcc, v49, v74
	s_nop 1
	v_cndmask_b32_e32 v49, v65, v49, vcc
	v_div_scale_f32 v65, s[6:7], v49, v49, 1.0
	v_rcp_f32_e32 v111, v65
	v_div_scale_f32 v112, vcc, 1.0, v49, 1.0
	v_fma_f32 v113, -v65, v111, 1.0
	v_fmac_f32_e32 v111, v113, v111
	v_mul_f32_e32 v113, v112, v111
	v_fma_f32 v114, -v65, v113, v112
	v_fmac_f32_e32 v113, v114, v111
	v_fma_f32 v65, -v65, v113, v112
	v_div_fmas_f32 v65, v65, v111, v113
	v_div_fixup_f32 v112, v65, v49, 1.0
	v_pk_mul_f32 v[28:29], v[28:29], v[112:113] op_sel_hi:[1,0]
	v_pk_mul_f32 v[114:115], v[30:31], v[112:113] op_sel_hi:[1,0]
	v_pk_mul_f32 v[116:117], v[32:33], v[112:113] op_sel_hi:[1,0]
	v_pk_mul_f32 v[112:113], v[26:27], v[112:113] op_sel_hi:[1,0]
	s_andn2_b64 vcc, exec, s[24:25]
	v_pk_mul_f32 v[30:31], v[22:23], v[28:29]
	v_pk_mul_f32 v[32:33], v[24:25], v[114:115]
	v_pk_mul_f32 v[26:27], v[18:19], v[116:117]
	v_pk_mul_f32 v[28:29], v[20:21], v[112:113]
	s_cbranch_vccnz .LBB0_981
	v_lshlrev_b64 v[70:71], 11, v[70:71]
	v_lshl_add_u64 v[70:71], s[18:19], 0, v[70:71]
	s_lshl_b32 s16, s40, 2
	v_lshl_add_u64 v[70:71], v[70:71], 0, s[16:17]
	v_lshl_add_u64 v[70:71], v[70:71], 0, v[36:37]
	v_lshl_add_u64 v[112:113], v[70:71], 0, s[22:23]
	v_add_co_u32_e32 v70, vcc, 0xfc000000, v70
	s_nop 1
	v_addc_co_u32_e32 v71, vcc, -1, v71, vcc
	global_store_dwordx4 v[70:71], v[30:33], off
	global_store_dwordx4 v[112:113], v[26:29], off offset:16
.LBB0_981:
	v_or_b32_e32 v70, s41, v72
	v_ashrrev_i32_e32 v71, 31, v70
	v_lshlrev_b64 v[112:113], 6, v[70:71]
	v_lshlrev_b64 v[124:125], 10, v[70:71]
	v_lshl_add_u64 v[126:127], s[14:15], 0, v[112:113]
	s_waitcnt vmcnt(5)
	v_mov_b32_e32 v112, v184
	v_mov_b32_e32 v113, v185
	v_mov_b32_e32 v114, v186
	v_mov_b32_e32 v115, v187
	v_mov_b32_e32 v116, v188
	v_mov_b32_e32 v117, v189
	v_mov_b32_e32 v118, v190
	v_mov_b32_e32 v119, v191
	v_mov_b32_e32 v120, v198
	v_mov_b32_e32 v121, v199
	v_mov_b32_e32 v122, v200
	v_mov_b32_e32 v123, v201
	v_lshl_add_u64 v[128:129], v[68:69], 0, v[124:125]
	v_mov_b32_e32 v124, v202
	v_mov_b32_e32 v125, v203
	v_mov_b32_e32 v126, v204
	v_mov_b32_e32 v127, v205
	s_nop 0
	v_mov_b32_e32 v128, v206
	v_mov_b32_e32 v129, v207
	v_mov_b32_e32 v130, v208
	v_mov_b32_e32 v131, v209
	v_bfe_u32 v49, v30, 16, 1
	v_bfe_u32 v65, v31, 16, 1
	v_bfe_u32 v111, v32, 16, 1
	v_bfe_u32 v132, v33, 16, 1
	v_bfe_u32 v133, v26, 16, 1
	v_bfe_u32 v134, v27, 16, 1
	v_bfe_u32 v135, v28, 16, 1
	v_bfe_u32 v136, v29, 16, 1
	v_add3_u32 v30, v30, v49, s28
	v_add3_u32 v31, v31, v65, s28
	v_add3_u32 v32, v32, v111, s28
	v_add3_u32 v33, v33, v132, s28
	v_add3_u32 v26, v26, v133, s28
	v_add3_u32 v27, v27, v134, s28
	v_add3_u32 v28, v28, v135, s28
	v_add3_u32 v29, v29, v136, s28
	ds_write_b16_d16_hi v76, v30
	ds_write_b16_d16_hi v76, v31 offset:272
	ds_write_b16_d16_hi v76, v32 offset:544
	ds_write_b16_d16_hi v76, v33 offset:816
	ds_write_b16_d16_hi v76, v26 offset:1088
	ds_write_b16_d16_hi v76, v27 offset:1360
	ds_write_b16_d16_hi v76, v28 offset:1632
	ds_write_b16_d16_hi v76, v29 offset:1904
	v_pk_add_f32 v[26:27], v[112:113], v[114:115]
	v_pk_add_f32 v[30:31], v[116:117], v[118:119]
	v_pk_add_f32 v[28:29], v[120:121], v[122:123]
	v_pk_add_f32 v[32:33], v[124:125], v[126:127]
	v_pk_add_f32 v[26:27], v[26:27], v[28:29]
	v_pk_add_f32 v[28:29], v[30:31], v[32:33]
	v_lshlrev_b32_e32 v112, 16, v128
	v_pk_add_f32 v[26:27], v[26:27], v[28:29]
	v_and_b32_e32 v113, 0xffff0000, v128
	v_pk_mul_f32 v[26:27], v[26:27], s[20:21] op_sel_hi:[1,0]
	v_lshlrev_b32_e32 v114, 16, v129
	v_fma_f32 v28, -v26, v26, v27
	v_max_f32_e32 v28, 0, v28
	v_add_f32_e32 v28, 0x358637bd, v28
	v_mul_f32_e32 v29, 0x4f800000, v28
	v_cmp_gt_f32_e32 vcc, s30, v28
	v_and_b32_e32 v115, 0xffff0000, v129
	v_pk_add_f32 v[30:31], v[114:115], v[26:27] op_sel_hi:[1,0] neg_lo:[0,1] neg_hi:[0,1]
	v_cndmask_b32_e32 v49, v28, v29, vcc
	v_sqrt_f32_e32 v65, v49
	v_pk_add_f32 v[28:29], v[112:113], v[26:27] op_sel_hi:[1,0] neg_lo:[0,1] neg_hi:[0,1]
	v_lshlrev_b32_e32 v116, 16, v130
	v_and_b32_e32 v117, 0xffff0000, v130
	v_add_u32_e32 v111, -1, v65
	v_add_u32_e32 v112, 1, v65
	v_fma_f32 v113, -v111, v65, v49
	v_fma_f32 v114, -v112, v65, v49
	v_cmp_ge_f32_e64 s[6:7], 0, v113
	v_lshlrev_b32_e32 v118, 16, v131
	v_and_b32_e32 v119, 0xffff0000, v131
	v_cndmask_b32_e64 v65, v65, v111, s[6:7]
	v_cmp_lt_f32_e64 s[6:7], 0, v114
	v_pk_add_f32 v[32:33], v[116:117], v[26:27] op_sel_hi:[1,0] neg_lo:[0,1] neg_hi:[0,1]
	v_pk_add_f32 v[26:27], v[118:119], v[26:27] op_sel_hi:[1,0] neg_lo:[0,1] neg_hi:[0,1]
	v_cndmask_b32_e64 v65, v65, v112, s[6:7]
	v_mul_f32_e32 v111, 0x37800000, v65
	v_cndmask_b32_e32 v65, v65, v111, vcc
	v_cmp_class_f32_e32 vcc, v49, v74
	s_nop 1
	v_cndmask_b32_e32 v49, v65, v49, vcc
	v_div_scale_f32 v65, s[6:7], v49, v49, 1.0
	v_rcp_f32_e32 v111, v65
	v_div_scale_f32 v112, vcc, 1.0, v49, 1.0
	v_fma_f32 v113, -v65, v111, 1.0
	v_fmac_f32_e32 v111, v113, v111
	v_mul_f32_e32 v113, v112, v111
	v_fma_f32 v114, -v65, v113, v112
	v_fmac_f32_e32 v113, v114, v111
	v_fma_f32 v65, -v65, v113, v112
	v_div_fmas_f32 v65, v65, v111, v113
	v_div_fixup_f32 v112, v65, v49, 1.0
	v_pk_mul_f32 v[28:29], v[28:29], v[112:113] op_sel_hi:[1,0]
	v_pk_mul_f32 v[114:115], v[30:31], v[112:113] op_sel_hi:[1,0]
	v_pk_mul_f32 v[116:117], v[32:33], v[112:113] op_sel_hi:[1,0]
	v_pk_mul_f32 v[112:113], v[26:27], v[112:113] op_sel_hi:[1,0]
	s_and_b64 vcc, exec, s[0:1]
	v_pk_mul_f32 v[30:31], v[22:23], v[28:29]
	v_pk_mul_f32 v[32:33], v[24:25], v[114:115]
	v_pk_mul_f32 v[26:27], v[18:19], v[116:117]
	v_pk_mul_f32 v[28:29], v[20:21], v[112:113]
	s_cbranch_vccnz .LBB0_983
	v_lshlrev_b64 v[70:71], 11, v[70:71]
	v_lshl_add_u64 v[70:71], s[18:19], 0, v[70:71]
	s_lshl_b32 s16, s40, 2
	v_lshl_add_u64 v[70:71], v[70:71], 0, s[16:17]
	v_lshl_add_u64 v[70:71], v[70:71], 0, v[36:37]
	v_lshl_add_u64 v[112:113], v[70:71], 0, s[22:23]
	v_add_co_u32_e32 v70, vcc, 0xfc000000, v70
	s_nop 1
	v_addc_co_u32_e32 v71, vcc, -1, v71, vcc
	global_store_dwordx4 v[70:71], v[30:33], off
	global_store_dwordx4 v[112:113], v[26:29], off offset:16
.LBB0_983:
	v_add_u32_e32 v70, s41, v73
	v_ashrrev_i32_e32 v71, 31, v70
	v_lshlrev_b64 v[112:113], 6, v[70:71]
	v_lshl_add_u64 v[126:127], s[14:15], 0, v[112:113]
	v_lshlrev_b64 v[124:125], 10, v[70:71]
	s_waitcnt vmcnt(0)
	v_mov_b32_e32 v112, v212
	v_mov_b32_e32 v113, v213
	v_mov_b32_e32 v114, v214
	v_mov_b32_e32 v115, v215
	v_mov_b32_e32 v116, v220
	v_mov_b32_e32 v117, v221
	v_mov_b32_e32 v118, v222
	v_mov_b32_e32 v119, v223
	v_mov_b32_e32 v120, v224
	v_mov_b32_e32 v121, v225
	v_mov_b32_e32 v122, v226
	v_mov_b32_e32 v123, v227
	v_lshl_add_u64 v[68:69], v[68:69], 0, v[124:125]
	v_mov_b32_e32 v124, v228
	v_mov_b32_e32 v125, v229
	v_mov_b32_e32 v126, v230
	v_mov_b32_e32 v127, v231
	s_nop 0
	v_mov_b32_e32 v128, v232
	v_mov_b32_e32 v129, v233
	v_mov_b32_e32 v130, v234
	v_mov_b32_e32 v131, v235
	v_bfe_u32 v49, v30, 16, 1
	v_bfe_u32 v65, v31, 16, 1
	v_bfe_u32 v68, v32, 16, 1
	v_bfe_u32 v69, v33, 16, 1
	v_bfe_u32 v111, v26, 16, 1
	v_bfe_u32 v132, v27, 16, 1
	v_bfe_u32 v133, v28, 16, 1
	v_bfe_u32 v134, v29, 16, 1
	v_add3_u32 v30, v30, v49, s28
	v_add3_u32 v31, v31, v65, s28
	v_add3_u32 v32, v32, v68, s28
	v_add3_u32 v33, v33, v69, s28
	v_add3_u32 v26, v26, v111, s28
	v_add3_u32 v27, v27, v132, s28
	v_add3_u32 v28, v28, v133, s28
	v_add3_u32 v29, v29, v134, s28
	ds_write_b16_d16_hi v77, v30
	ds_write_b16_d16_hi v77, v31 offset:272
	ds_write_b16_d16_hi v77, v32 offset:544
	ds_write_b16_d16_hi v77, v33 offset:816
	ds_write_b16_d16_hi v77, v26 offset:1088
	ds_write_b16_d16_hi v77, v27 offset:1360
	ds_write_b16_d16_hi v77, v28 offset:1632
	ds_write_b16_d16_hi v77, v29 offset:1904
	v_pk_add_f32 v[26:27], v[112:113], v[114:115]
	v_pk_add_f32 v[30:31], v[116:117], v[118:119]
	v_pk_add_f32 v[28:29], v[120:121], v[122:123]
	v_pk_add_f32 v[32:33], v[124:125], v[126:127]
	v_pk_add_f32 v[26:27], v[26:27], v[28:29]
	v_pk_add_f32 v[28:29], v[30:31], v[32:33]
	v_lshlrev_b32_e32 v68, 16, v128
	v_pk_add_f32 v[26:27], v[26:27], v[28:29]
	v_and_b32_e32 v69, 0xffff0000, v128
	v_pk_mul_f32 v[26:27], v[26:27], s[20:21] op_sel_hi:[1,0]
	v_lshlrev_b32_e32 v112, 16, v129
	v_fma_f32 v28, -v26, v26, v27
	v_max_f32_e32 v28, 0, v28
	v_add_f32_e32 v28, 0x358637bd, v28
	v_mul_f32_e32 v29, 0x4f800000, v28
	v_cmp_gt_f32_e32 vcc, s30, v28
	v_and_b32_e32 v113, 0xffff0000, v129
	v_pk_add_f32 v[30:31], v[112:113], v[26:27] op_sel_hi:[1,0] neg_lo:[0,1] neg_hi:[0,1]
	v_cndmask_b32_e32 v49, v28, v29, vcc
	v_sqrt_f32_e32 v65, v49
	v_pk_add_f32 v[28:29], v[68:69], v[26:27] op_sel_hi:[1,0] neg_lo:[0,1] neg_hi:[0,1]
	v_lshlrev_b32_e32 v114, 16, v130
	v_and_b32_e32 v115, 0xffff0000, v130
	v_add_u32_e32 v68, -1, v65
	v_add_u32_e32 v69, 1, v65
	v_fma_f32 v111, -v68, v65, v49
	v_fma_f32 v112, -v69, v65, v49
	v_cmp_ge_f32_e64 s[6:7], 0, v111
	v_lshlrev_b32_e32 v116, 16, v131
	v_and_b32_e32 v117, 0xffff0000, v131
	v_cndmask_b32_e64 v65, v65, v68, s[6:7]
	v_cmp_lt_f32_e64 s[6:7], 0, v112
	v_pk_add_f32 v[32:33], v[114:115], v[26:27] op_sel_hi:[1,0] neg_lo:[0,1] neg_hi:[0,1]
	v_pk_add_f32 v[26:27], v[116:117], v[26:27] op_sel_hi:[1,0] neg_lo:[0,1] neg_hi:[0,1]
	v_cndmask_b32_e64 v65, v65, v69, s[6:7]
	v_mul_f32_e32 v68, 0x37800000, v65
	v_cndmask_b32_e32 v65, v65, v68, vcc
	v_cmp_class_f32_e32 vcc, v49, v74
	s_nop 1
	v_cndmask_b32_e32 v49, v65, v49, vcc
	v_div_scale_f32 v65, s[6:7], v49, v49, 1.0
	v_rcp_f32_e32 v68, v65
	v_div_scale_f32 v69, vcc, 1.0, v49, 1.0
	v_fma_f32 v111, -v65, v68, 1.0
	v_fmac_f32_e32 v68, v111, v68
	v_mul_f32_e32 v111, v69, v68
	v_fma_f32 v112, -v65, v111, v69
	v_fmac_f32_e32 v111, v112, v68
	v_fma_f32 v65, -v65, v111, v69
	v_div_fmas_f32 v65, v65, v68, v111
	v_div_fixup_f32 v68, v65, v49, 1.0
	v_pk_mul_f32 v[28:29], v[28:29], v[68:69] op_sel_hi:[1,0]
	v_pk_mul_f32 v[30:31], v[30:31], v[68:69] op_sel_hi:[1,0]
	v_pk_mul_f32 v[32:33], v[32:33], v[68:69] op_sel_hi:[1,0]
	v_pk_mul_f32 v[26:27], v[26:27], v[68:69] op_sel_hi:[1,0]
	s_and_b64 vcc, exec, s[0:1]
	v_pk_mul_f32 v[22:23], v[22:23], v[28:29]
	v_pk_mul_f32 v[24:25], v[24:25], v[30:31]
	v_pk_mul_f32 v[18:19], v[18:19], v[32:33]
	v_pk_mul_f32 v[20:21], v[20:21], v[26:27]
	v_mov_b32_e32 v26, v34
	s_cbranch_vccnz .LBB0_976
	v_lshlrev_b64 v[26:27], 11, v[70:71]
	v_lshl_add_u64 v[26:27], s[18:19], 0, v[26:27]
	s_lshl_b32 s16, s40, 2
	v_lshl_add_u64 v[26:27], v[26:27], 0, s[16:17]
	v_lshl_add_u64 v[26:27], v[26:27], 0, v[36:37]
	v_lshl_add_u64 v[28:29], v[26:27], 0, s[22:23]
	v_add_co_u32_e32 v26, vcc, 0xfc000000, v26
	s_nop 1
	v_addc_co_u32_e32 v27, vcc, -1, v27, vcc
	global_store_dwordx4 v[26:27], v[22:25], off
	global_store_dwordx4 v[28:29], v[18:21], off offset:16
	v_mov_b32_e32 v26, v41
	s_branch .LBB0_976
